# attention: branch-free batched rel-pos-bias lookups on diagonal tiles; softmax-side setprio; packed f32 adds split; ret_out gate ladder pipelined
# speedup vs baseline: 1.0318x; 1.0260x over previous
;     ...
;             if (t < NTw) AT_QKB(t & 1);
.LBB0_304:
	s_cmp_lt_i32 s4, 0
	s_cbranch_scc1 .LBB0_307
	s_or_b32 s34, s18, 31
	s_cmpk_lt_i32 s34, 0xffc1
	s_cselect_b64 s[6:7], -1, 0
	s_and_b64 vcc, exec, s[6:7]
	s_cbranch_vccnz .LBB0_314
	ds_read_b128 v[0:3], v221
	ds_read_b128 v[4:7], v221 offset:8704
	ds_read_b128 v[34:37], v221 offset:32
	ds_read_b128 v[38:41], v221 offset:8736
	ds_read_b128 v[42:45], v221 offset:64
	ds_read_b128 v[50:53], v221 offset:8768
	s_waitcnt lgkmcnt(5)
	v_mfma_f32_32x32x16_bf16 v[16:31], v[0:3], v[144:147], 0
	s_waitcnt lgkmcnt(4)
	v_mfma_f32_32x32x16_bf16 v[0:15], v[4:7], v[144:147], 0
	ds_read_b128 v[54:57], v221 offset:96
	ds_read_b128 v[58:61], v221 offset:8800
	s_waitcnt lgkmcnt(5)
	v_mfma_f32_32x32x16_bf16 v[16:31], v[34:37], v[148:151], v[16:31]
	s_waitcnt lgkmcnt(4)
	v_mfma_f32_32x32x16_bf16 v[0:15], v[38:41], v[148:151], v[0:15]
	s_waitcnt lgkmcnt(3)
	v_mfma_f32_32x32x16_bf16 v[16:31], v[42:45], v[152:155], v[16:31]
	s_waitcnt lgkmcnt(2)
	v_mfma_f32_32x32x16_bf16 v[0:15], v[50:53], v[152:155], v[0:15]
	s_waitcnt lgkmcnt(1)
	v_mfma_f32_32x32x16_bf16 v[16:31], v[54:57], v[156:159], v[16:31]
	s_waitcnt lgkmcnt(0)
	v_mfma_f32_32x32x16_bf16 v[0:15], v[58:61], v[156:159], v[0:15]
	s_branch .LBB0_315

; #define AT_LOADK(t) do { kr0 = *(const v4u*)(kg + (size_t)(t) * 64 * 1024); kr1 = *(const v4u*)(kg + (size_t)(t) * 64 * 1024 + 32 * 1024); } while (0)
; #define AT_LOADV(t) do { vr0 = *(const v4u*)(vg + (t) * 64); vr1 = *(const v4u*)(vg + (size_t)64 * SEQ + (t) * 64); } while (0)
; #define AT_STOREK(bf) do { *(LAS v4u*)(lds + (bf) * AT_KBUF + kso) = kr0; *(LAS v4u*)(lds + (bf) * AT_KBUF + kso + 32 * AT_KSTR * 2) = kr1; } while (0)
; #define AT_STOREV(bf) do { *(LAS v2u*)(lds + (bf) * AT_VBUF + vso) = (v2u){vr0.x, vr0.y}; *(LAS v2u*)(lds + (bf) * AT_VBUF + vso + 8) = (v2u){vr0.z, vr0.w}; \
;         *(LAS v2u*)(lds + (bf) * AT_VBUF + vso + 64 * AT_VSTR * 2) = (v2u){vr1.x, vr1.y}; *(LAS v2u*)(lds + (bf) * AT_VBUF + vso + 64 * AT_VSTR * 2 + 8) = (v2u){vr1.z, vr1.w}; } while (0)
;     ...
;         __syncthreads();
;         AT_LOADK(0); AT_LOADV(0); AT_STOREK(0); AT_STOREV(0); AT_LOADK(1); AT_STOREK(1);
;         __syncthreads();
;         if (isY) __syncthreads();
.LBB0_308:
	v_lshlrev_b64 v[34:35], 10, v[212:213]
	s_and_b64 vcc, exec, s[26:27]
	s_setprio 0
	s_barrier
	s_cbranch_vccz .LBB0_310
	s_setprio 0
	s_barrier

; __device__ __forceinline__ int crow(int i, int hh) { return (i & 3) + 8 * (i >> 2) + 4 * hh; }
; __device__ __forceinline__ float xhalf_sum(float v) { const auto rr = __builtin_amdgcn_permlane32_swap(__float_as_uint(v), __float_as_uint(v), false, false); return __uint_as_float(rr[0]) + __uint_as_float(rr[1]); }
;     ...
;         __syncthreads();
;         if (!isY) __syncthreads();
;     ...
;         l = xhalf_sum(l);
;         const float linv = 1.0f / l;
;         if (mi == 1) { const float sc = lam * linv;
; #pragma unroll
;             for (int dt = 0; dt < 4; ++dt)
; #pragma unroll
;                 for (int i = 0; i < 16; ++i) ex[g * 4096 + (32 * dt + crow(i, hh)) * 32 + r] = o[dt][i] * sc; }
;         __syncthreads();
;         if (mi == 0) { float ssq = 0.f;
; #pragma unroll
;             for (int dt = 0; dt < 4; ++dt)
; #pragma unroll
;                 for (int i = 0; i < 16; ++i) { const float v = o[dt][i] * linv - ex[g * 4096 + (32 * dt + crow(i, hh)) * 32 + r]; o[dt][i] = v; ssq += v * v; }
.LBB0_312:
	s_andn2_b64 vcc, exec, s[28:29]
	s_waitcnt lgkmcnt(0)
	s_setprio 0
	s_barrier
	s_cbranch_vccnz .LBB0_296
	ds_read2_b32 v[38:39], v224 offset1:32
	ds_read2_b32 v[40:41], v42 offset1:32
	ds_read2_b32 v[42:43], v42 offset0:64 offset1:96
	s_waitcnt lgkmcnt(2)
	v_fma_f32 v37, v64, v36, -v38
	v_fma_f32 v33, v65, v36, -v39
	ds_read2_b32 v[38:39], v224 offset0:64 offset1:96
	ds_read2_b32 v[64:65], v46 offset1:32
	ds_read2_b32 v[46:47], v46 offset0:64 offset1:96
	s_waitcnt lgkmcnt(3)
	v_fma_f32 v42, v70, v36, -v42
	v_fma_f32 v43, v71, v36, -v43
	s_waitcnt lgkmcnt(2)
	v_fma_f32 v38, v66, v36, -v38
	v_fma_f32 v39, v67, v36, -v39
	ds_read2_b32 v[66:67], v93 offset1:32
	s_waitcnt lgkmcnt(2)
	v_fma_f32 v45, v72, v36, -v64
	v_fma_f32 v44, v73, v36, -v65
	s_waitcnt lgkmcnt(1)
	v_fma_f32 v65, v74, v36, -v46
	v_fma_f32 v64, v75, v36, -v47
	s_waitcnt lgkmcnt(0)
	v_fma_f32 v47, v76, v36, -v66
	v_fma_f32 v46, v77, v36, -v67
	ds_read2_b32 v[66:67], v93 offset0:64 offset1:96
	ds_read2_b32 v[70:71], v92 offset1:32
	v_fma_f32 v40, v68, v36, -v40
	v_fma_f32 v41, v69, v36, -v41
	ds_read2_b32 v[72:73], v90 offset1:32
	s_waitcnt lgkmcnt(2)
	v_fma_f32 v68, v78, v36, -v66
	s_waitcnt lgkmcnt(1)
	v_fma_f32 v66, v48, v36, -v70
	v_fma_f32 v48, v49, v36, -v71
	ds_read2_b32 v[70:71], v92 offset0:64 offset1:96
	v_mul_f32_e32 v84, v33, v33
	v_fmac_f32_e32 v84, v37, v37
	v_fmac_f32_e32 v84, v38, v38
	v_fmac_f32_e32 v84, v39, v39
	s_waitcnt lgkmcnt(0)
	v_fma_f32 v69, v50, v36, -v70
	v_fma_f32 v51, v51, v36, -v71
	ds_read2_b32 v[70:71], v91 offset1:32
	v_fmac_f32_e32 v84, v40, v40
	v_fmac_f32_e32 v84, v41, v41
	v_fmac_f32_e32 v84, v42, v42
	v_fmac_f32_e32 v84, v43, v43
	s_waitcnt lgkmcnt(0)
	v_fma_f32 v50, v52, v36, -v70
	v_fma_f32 v49, v53, v36, -v71
	ds_read2_b32 v[52:53], v91 offset0:64 offset1:96
	v_fmac_f32_e32 v84, v45, v45
	v_fmac_f32_e32 v84, v44, v44
	v_fmac_f32_e32 v84, v65, v65
	v_fmac_f32_e32 v84, v64, v64
	s_waitcnt lgkmcnt(0)
	v_fma_f32 v70, v54, v36, -v52
	v_fma_f32 v54, v55, v36, -v53
	v_fma_f32 v53, v56, v36, -v72
	v_fma_f32 v52, v57, v36, -v73
	ds_read2_b32 v[56:57], v90 offset0:64 offset1:96
	ds_read2_b32 v[72:73], v89 offset1:32
	v_fmac_f32_e32 v84, v47, v47
	v_fmac_f32_e32 v84, v46, v46
	v_fmac_f32_e32 v84, v68, v68
	s_waitcnt lgkmcnt(1)
	v_fma_f32 v58, v58, v36, -v56
	s_waitcnt lgkmcnt(0)
	v_fma_f32 v56, v60, v36, -v72
	v_fma_f32 v55, v61, v36, -v73
	ds_read2_b32 v[72:73], v89 offset0:64 offset1:96
	v_fma_f32 v57, v59, v36, -v57
	v_fma_f32 v67, v79, v36, -v67
	v_fmac_f32_e32 v84, v67, v67
	v_fmac_f32_e32 v84, v66, v66
	s_waitcnt lgkmcnt(0)
	v_fma_f32 v61, v62, v36, -v72
	v_fma_f32 v60, v63, v36, -v73
	ds_read2_b32 v[62:63], v88 offset1:32
	ds_read2_b32 v[72:73], v87 offset1:32
	v_fmac_f32_e32 v84, v48, v48
	v_fmac_f32_e32 v84, v69, v69
	v_fmac_f32_e32 v84, v51, v51
	s_waitcnt lgkmcnt(1)
	v_fma_f32 v59, v16, v36, -v62
	v_fma_f32 v16, v17, v36, -v63
	ds_read2_b32 v[62:63], v88 offset0:64 offset1:96
	s_waitcnt lgkmcnt(1)
	v_fma_f32 v17, v21, v36, -v73
	v_fmac_f32_e32 v84, v50, v50
	v_fmac_f32_e32 v84, v49, v49
	v_fmac_f32_e32 v84, v70, v70
	s_waitcnt lgkmcnt(0)
	v_fma_f32 v62, v18, v36, -v62
	v_fma_f32 v18, v20, v36, -v72
	ds_read2_b32 v[20:21], v87 offset0:64 offset1:96
	ds_read2_b32 v[72:73], v86 offset1:32
	v_fma_f32 v19, v19, v36, -v63
	v_fmac_f32_e32 v84, v54, v54
	v_fmac_f32_e32 v84, v53, v53
	s_waitcnt lgkmcnt(1)
	v_fma_f32 v63, v22, v36, -v20
	v_fma_f32 v22, v23, v36, -v21
	s_waitcnt lgkmcnt(0)
	v_fma_f32 v21, v24, v36, -v72
	v_fma_f32 v20, v25, v36, -v73
	ds_read2_b32 v[24:25], v86 offset0:64 offset1:96
	ds_read2_b32 v[72:73], v85 offset1:32
	v_fmac_f32_e32 v84, v52, v52
	v_fmac_f32_e32 v84, v58, v58
	v_fmac_f32_e32 v84, v57, v57
	s_waitcnt lgkmcnt(1)
	v_fma_f32 v26, v26, v36, -v24
	s_waitcnt lgkmcnt(0)
	v_fma_f32 v24, v28, v36, -v72
	v_fma_f32 v23, v29, v36, -v73
	ds_read2_b32 v[28:29], v85 offset0:64 offset1:96
	ds_read2_b32 v[72:73], v83 offset1:32
	v_fmac_f32_e32 v84, v56, v56
	v_fma_f32 v25, v27, v36, -v25
	v_fmac_f32_e32 v84, v55, v55
	s_waitcnt lgkmcnt(1)
	v_fma_f32 v71, v30, v36, -v28
	v_fma_f32 v30, v31, v36, -v29
	s_waitcnt lgkmcnt(0)
	v_fma_f32 v29, v0, v36, -v72
	v_fma_f32 v27, v1, v36, -v73
	ds_read2_b32 v[0:1], v83 offset0:64 offset1:96
	v_fmac_f32_e32 v84, v61, v61
	v_fmac_f32_e32 v84, v60, v60
	v_fmac_f32_e32 v84, v59, v59
	v_fmac_f32_e32 v84, v16, v16
	s_waitcnt lgkmcnt(0)
	v_fma_f32 v77, v2, v36, -v0
	v_fma_f32 v76, v3, v36, -v1
	ds_read2_b32 v[0:1], v82 offset1:32
	v_fmac_f32_e32 v84, v62, v62
	v_fmac_f32_e32 v84, v19, v19
	v_fmac_f32_e32 v84, v18, v18
	v_fmac_f32_e32 v84, v17, v17
	v_fmac_f32_e32 v84, v63, v63
	s_waitcnt lgkmcnt(0)
	v_fma_f32 v74, v4, v36, -v0
	v_fma_f32 v73, v5, v36, -v1
	ds_read2_b32 v[0:1], v82 offset0:64 offset1:96
	v_fmac_f32_e32 v84, v22, v22
	v_fmac_f32_e32 v84, v21, v21
	v_fmac_f32_e32 v84, v20, v20
	v_fmac_f32_e32 v84, v26, v26
	v_fmac_f32_e32 v84, v25, v25
	s_waitcnt lgkmcnt(0)
	v_fma_f32 v78, v6, v36, -v0
	v_fma_f32 v75, v7, v36, -v1
	ds_read2_b32 v[0:1], v81 offset1:32
	v_fmac_f32_e32 v84, v24, v24
	v_fmac_f32_e32 v84, v23, v23
	v_fmac_f32_e32 v84, v71, v71
	v_fmac_f32_e32 v84, v30, v30
	v_fmac_f32_e32 v84, v29, v29
	s_waitcnt lgkmcnt(0)
	v_fma_f32 v72, v8, v36, -v0
	v_fma_f32 v31, v9, v36, -v1
	ds_read2_b32 v[0:1], v81 offset0:64 offset1:96
	v_fmac_f32_e32 v84, v27, v27
	v_fmac_f32_e32 v84, v77, v77
	v_fmac_f32_e32 v84, v76, v76
	v_fmac_f32_e32 v84, v74, v74
	v_fmac_f32_e32 v84, v73, v73
	s_waitcnt lgkmcnt(0)
	v_fma_f32 v28, v10, v36, -v0
	v_fma_f32 v10, v11, v36, -v1
	ds_read2_b32 v[0:1], v80 offset1:32
	v_fmac_f32_e32 v84, v78, v78
	v_fmac_f32_e32 v84, v75, v75
	v_fmac_f32_e32 v84, v72, v72
	v_fmac_f32_e32 v84, v31, v31
	v_fmac_f32_e32 v84, v28, v28
	s_waitcnt lgkmcnt(0)
; __device__ __forceinline__ unsigned cvtpk(float lo, float hi) { return pg8::cvt_pk_bf16(lo, hi); }
;     ...
;             ssq += __shfl_xor(ssq, 32);
;             const float rstd = outscale / sqrtf(ssq * (1.0f / 128.0f) + RMS_EPS);
;             bf16* op = Od + ((size_t)(b * SEQ + qabs)) * 1024 + h * 128 + 4 * hh;
; #pragma unroll
;             for (int dt = 0; dt < 4; ++dt)
; #pragma unroll
;                 for (int i4 = 0; i4 < 4; ++i4) { const int dv = 32 * dt + 8 * i4; const f32x4 sg = *(const f32x4*)(subln + dv + 4 * hh);
;                     v2u wv; wv.x = cvtpk(o[dt][4 * i4] * rstd * sg[0], o[dt][4 * i4 + 1] * rstd * sg[1]); wv.y = cvtpk(o[dt][4 * i4 + 2] * rstd * sg[2], o[dt][4 * i4 + 3] * rstd * sg[3]);
;                     *(v2u*)(op + dv) = wv; }
	v_pk_fma_f32 v[6:7], v[12:13], v[36:37], v[0:1] op_sel_hi:[1,0,1] neg_lo:[0,0,1] neg_hi:[0,0,1]
	v_fmac_f32_e32 v84, v10, v10
	v_pk_mul_f32 v[0:1], v[6:7], v[6:7]
	s_nop 0
	v_add_f32_e32 v0, v84, v0
	v_add_f32_e32 v2, v0, v1
	ds_read2_b32 v[0:1], v80 offset0:64 offset1:96
	s_waitcnt lgkmcnt(0)
	v_pk_fma_f32 v[4:5], v[14:15], v[36:37], v[0:1] op_sel_hi:[1,0,1] neg_lo:[0,0,1] neg_hi:[0,0,1]
	s_nop 0
	v_pk_mul_f32 v[0:1], v[4:5], v[4:5]
	s_nop 0
	v_add_f32_e32 v0, v2, v0
	v_and_b32_e32 v2, 64, v233
	v_add_f32_e32 v0, v0, v1
	v_xor_b32_e32 v1, 32, v233
	v_add_u32_e32 v2, 64, v2
	v_cmp_lt_i32_e32 vcc, v1, v2
	s_nop 1
	v_cndmask_b32_e32 v1, v233, v1, vcc
	v_lshlrev_b32_e32 v1, 2, v1
	ds_bpermute_b32 v1, v1, v0
	s_waitcnt lgkmcnt(0)
	v_add_f32_e32 v0, v0, v1
	v_fmamk_f32 v0, v0, 0x3c000000, v231
	v_cmp_gt_f32_e32 vcc, s73, v0
	v_mul_f32_e32 v1, 0x4f800000, v0
	s_nop 0
	v_cndmask_b32_e32 v0, v0, v1, vcc
	v_sqrt_f32_e32 v1, v0
	s_nop 0
	v_add_u32_e32 v2, -1, v1
	v_fma_f32 v3, -v2, v1, v0
	v_cmp_ge_f32_e64 s[40:41], 0, v3
	v_add_u32_e32 v3, 1, v1
	s_nop 0
	v_cndmask_b32_e64 v2, v1, v2, s[40:41]
	v_fma_f32 v1, -v3, v1, v0
	v_cmp_lt_f32_e64 s[40:41], 0, v1
	s_nop 1
	v_cndmask_b32_e64 v1, v2, v3, s[40:41]
	v_mul_f32_e32 v2, 0x37800000, v1
	v_cndmask_b32_e32 v1, v1, v2, vcc
	v_cmp_class_f32_e32 vcc, v0, v232
	s_nop 1
	v_cndmask_b32_e32 v0, v1, v0, vcc
	v_div_scale_f32 v1, s[4:5], v0, v0, v215
	v_rcp_f32_e32 v2, v1
	s_nop 0
	v_fma_f32 v3, -v1, v2, 1.0
	v_fmac_f32_e32 v2, v3, v2
	v_div_scale_f32 v3, vcc, v215, v0, v215
	v_mul_f32_e32 v8, v3, v2
	v_fma_f32 v9, -v1, v8, v3
	v_fmac_f32_e32 v8, v9, v2
	v_fma_f32 v1, -v1, v8, v3
	v_div_fmas_f32 v1, v1, v2, v8
	v_div_fixup_f32 v11, v1, v0, v215
	global_load_dwordx4 v[0:3], v[192:193], off
	v_mul_f32_e32 v12, v37, v11
	v_lshl_add_u64 v[8:9], v[34:35], 1, v[190:191]
	v_mul_f32_e32 v6, v6, v11
	s_waitcnt vmcnt(0)
	v_mul_f32_e32 v0, v0, v12
	v_mul_f32_e32 v12, v33, v11
	v_mul_f32_e32 v1, v1, v12
	v_cvt_pk_bf16_f32 v0, v0, v1
	v_mul_f32_e32 v1, v38, v11
	v_mul_f32_e32 v1, v2, v1
	v_mul_f32_e32 v2, v39, v11
	v_mul_f32_e32 v2, v3, v2
	v_cvt_pk_bf16_f32 v1, v1, v2
	global_store_dwordx2 v[8:9], v[0:1], off
	global_load_dwordx4 v[0:3], v[192:193], off offset:32
	v_mul_f32_e32 v12, v40, v11
	s_waitcnt vmcnt(0)
	v_mul_f32_e32 v0, v0, v12
	v_mul_f32_e32 v12, v41, v11
	v_mul_f32_e32 v1, v1, v12
	v_cvt_pk_bf16_f32 v0, v0, v1
	v_mul_f32_e32 v1, v42, v11
	v_mul_f32_e32 v1, v2, v1
	v_mul_f32_e32 v2, v43, v11
	v_mul_f32_e32 v2, v3, v2
	v_cvt_pk_bf16_f32 v1, v1, v2
	global_store_dwordx2 v[8:9], v[0:1], off offset:16
	global_load_dwordx4 v[0:3], v[192:193], off offset:64
	v_mul_f32_e32 v12, v45, v11
	s_waitcnt vmcnt(0)
	v_mul_f32_e32 v0, v12, v0
	v_mul_f32_e32 v12, v44, v11
	v_mul_f32_e32 v1, v12, v1
	v_cvt_pk_bf16_f32 v0, v0, v1
	v_mul_f32_e32 v1, v65, v11
	v_mul_f32_e32 v1, v1, v2
	v_mul_f32_e32 v2, v64, v11
	v_mul_f32_e32 v2, v2, v3
	v_cvt_pk_bf16_f32 v1, v1, v2
	global_store_dwordx2 v[8:9], v[0:1], off offset:32
	global_load_dwordx4 v[0:3], v[192:193], off offset:96
	v_mul_f32_e32 v12, v47, v11
	s_waitcnt vmcnt(0)
	v_mul_f32_e32 v0, v12, v0
	v_mul_f32_e32 v12, v46, v11
	v_mul_f32_e32 v1, v12, v1
	v_cvt_pk_bf16_f32 v0, v0, v1
	v_mul_f32_e32 v1, v68, v11
	v_mul_f32_e32 v1, v1, v2
	v_mul_f32_e32 v2, v67, v11
	v_mul_f32_e32 v2, v2, v3
	v_cvt_pk_bf16_f32 v1, v1, v2
	global_store_dwordx2 v[8:9], v[0:1], off offset:48
	global_load_dwordx4 v[0:3], v[192:193], off offset:128
	v_mul_f32_e32 v12, v66, v11
	s_waitcnt vmcnt(0)
	v_mul_f32_e32 v0, v12, v0
	v_mul_f32_e32 v12, v48, v11
	v_mul_f32_e32 v1, v12, v1
	v_cvt_pk_bf16_f32 v0, v0, v1
	v_mul_f32_e32 v1, v69, v11
	v_mul_f32_e32 v1, v1, v2
	v_mul_f32_e32 v2, v51, v11
	v_mul_f32_e32 v2, v2, v3
	v_cvt_pk_bf16_f32 v1, v1, v2
	global_store_dwordx2 v[8:9], v[0:1], off offset:64
	global_load_dwordx4 v[0:3], v[192:193], off offset:160
	v_mul_f32_e32 v12, v50, v11
	s_waitcnt vmcnt(0)
	v_mul_f32_e32 v0, v12, v0
	v_mul_f32_e32 v12, v49, v11
	v_mul_f32_e32 v1, v12, v1
	v_cvt_pk_bf16_f32 v0, v0, v1
	v_mul_f32_e32 v1, v70, v11
	v_mul_f32_e32 v1, v1, v2
	v_mul_f32_e32 v2, v54, v11
	v_mul_f32_e32 v2, v2, v3
	v_cvt_pk_bf16_f32 v1, v1, v2
	global_store_dwordx2 v[8:9], v[0:1], off offset:80
	global_load_dwordx4 v[0:3], v[192:193], off offset:192
	v_mul_f32_e32 v12, v53, v11
	s_waitcnt vmcnt(0)
; __device__ __forceinline__ unsigned cvtpk(float lo, float hi) { return pg8::cvt_pk_bf16(lo, hi); }
;     ...
;             for (int dt = 0; dt < 4; ++dt)
; #pragma unroll
;                 for (int i4 = 0; i4 < 4; ++i4) { const int dv = 32 * dt + 8 * i4; const f32x4 sg = *(const f32x4*)(subln + dv + 4 * hh);
;                     v2u wv; wv.x = cvtpk(o[dt][4 * i4] * rstd * sg[0], o[dt][4 * i4 + 1] * rstd * sg[1]); wv.y = cvtpk(o[dt][4 * i4 + 2] * rstd * sg[2], o[dt][4 * i4 + 3] * rstd * sg[3]);
;                     *(v2u*)(op + dv) = wv; }
	v_mul_f32_e32 v0, v12, v0
	v_mul_f32_e32 v12, v52, v11
	v_mul_f32_e32 v1, v12, v1
	v_cvt_pk_bf16_f32 v0, v0, v1
	v_mul_f32_e32 v1, v58, v11
	v_mul_f32_e32 v1, v1, v2
	v_mul_f32_e32 v2, v57, v11
	v_mul_f32_e32 v2, v2, v3
	v_cvt_pk_bf16_f32 v1, v1, v2
	global_store_dwordx2 v[8:9], v[0:1], off offset:96
	global_load_dwordx4 v[0:3], v[192:193], off offset:224
	v_mul_f32_e32 v12, v56, v11
	s_waitcnt vmcnt(0)
	v_mul_f32_e32 v0, v12, v0
	v_mul_f32_e32 v12, v55, v11
	v_mul_f32_e32 v1, v12, v1
	v_cvt_pk_bf16_f32 v0, v0, v1
	v_mul_f32_e32 v1, v61, v11
	v_mul_f32_e32 v1, v1, v2
	v_mul_f32_e32 v2, v60, v11
	v_mul_f32_e32 v2, v2, v3
	v_cvt_pk_bf16_f32 v1, v1, v2
	global_store_dwordx2 v[8:9], v[0:1], off offset:112
	global_load_dwordx4 v[0:3], v[192:193], off offset:256
	v_mul_f32_e32 v12, v59, v11
	s_waitcnt vmcnt(0)
	v_mul_f32_e32 v0, v12, v0
	v_mul_f32_e32 v12, v16, v11
	v_mul_f32_e32 v1, v12, v1
	v_cvt_pk_bf16_f32 v0, v0, v1
	v_mul_f32_e32 v1, v62, v11
	v_mul_f32_e32 v1, v1, v2
	v_mul_f32_e32 v2, v19, v11
	v_mul_f32_e32 v2, v2, v3
	v_cvt_pk_bf16_f32 v1, v1, v2
	global_store_dwordx2 v[8:9], v[0:1], off offset:128
	global_load_dwordx4 v[0:3], v[192:193], off offset:288
	v_mul_f32_e32 v12, v18, v11
	s_waitcnt vmcnt(0)
	v_mul_f32_e32 v0, v12, v0
	v_mul_f32_e32 v12, v17, v11
	v_mul_f32_e32 v1, v12, v1
	v_cvt_pk_bf16_f32 v0, v0, v1
	v_mul_f32_e32 v1, v63, v11
	v_mul_f32_e32 v1, v1, v2
	v_mul_f32_e32 v2, v22, v11
	v_mul_f32_e32 v2, v2, v3
	v_cvt_pk_bf16_f32 v1, v1, v2
	global_store_dwordx2 v[8:9], v[0:1], off offset:144
	global_load_dwordx4 v[0:3], v[192:193], off offset:320
	v_mul_f32_e32 v12, v21, v11
	s_waitcnt vmcnt(0)
	v_mul_f32_e32 v0, v12, v0
	v_mul_f32_e32 v12, v20, v11
	v_mul_f32_e32 v1, v12, v1
	v_cvt_pk_bf16_f32 v0, v0, v1
	v_mul_f32_e32 v1, v26, v11
	v_mul_f32_e32 v1, v1, v2
	v_mul_f32_e32 v2, v25, v11
	v_mul_f32_e32 v2, v2, v3
	v_cvt_pk_bf16_f32 v1, v1, v2
	global_store_dwordx2 v[8:9], v[0:1], off offset:160
	global_load_dwordx4 v[0:3], v[192:193], off offset:352
	v_mul_f32_e32 v12, v24, v11
	s_waitcnt vmcnt(0)
	v_mul_f32_e32 v0, v12, v0
	v_mul_f32_e32 v12, v23, v11
	v_mul_f32_e32 v1, v12, v1
	v_cvt_pk_bf16_f32 v0, v0, v1
	v_mul_f32_e32 v1, v71, v11
	v_mul_f32_e32 v1, v1, v2
	v_mul_f32_e32 v2, v30, v11
	v_mul_f32_e32 v2, v2, v3
	v_cvt_pk_bf16_f32 v1, v1, v2
	global_store_dwordx2 v[8:9], v[0:1], off offset:176
	global_load_dwordx4 v[0:3], v[192:193], off offset:384
	v_mul_f32_e32 v12, v29, v11
	s_waitcnt vmcnt(0)
	v_mul_f32_e32 v0, v12, v0
	v_mul_f32_e32 v12, v27, v11
	v_mul_f32_e32 v1, v12, v1
	v_cvt_pk_bf16_f32 v0, v0, v1
	v_mul_f32_e32 v1, v77, v11
	v_mul_f32_e32 v1, v1, v2
	v_mul_f32_e32 v2, v76, v11
	v_mul_f32_e32 v2, v2, v3
	v_cvt_pk_bf16_f32 v1, v1, v2
	global_store_dwordx2 v[8:9], v[0:1], off offset:192
	global_load_dwordx4 v[0:3], v[192:193], off offset:416
	v_mul_f32_e32 v12, v74, v11
	s_waitcnt vmcnt(0)
	v_mul_f32_e32 v0, v12, v0
	v_mul_f32_e32 v12, v73, v11
	v_mul_f32_e32 v1, v12, v1
	v_cvt_pk_bf16_f32 v0, v0, v1
	v_mul_f32_e32 v1, v78, v11
	v_mul_f32_e32 v1, v1, v2
	v_mul_f32_e32 v2, v75, v11
	v_mul_f32_e32 v2, v2, v3
	v_cvt_pk_bf16_f32 v1, v1, v2
	global_store_dwordx2 v[8:9], v[0:1], off offset:208
	global_load_dwordx4 v[0:3], v[192:193], off offset:448
	v_mul_f32_e32 v12, v72, v11
	s_waitcnt vmcnt(0)
	v_mul_f32_e32 v0, v12, v0
	v_mul_f32_e32 v12, v31, v11
	v_mul_f32_e32 v1, v12, v1
	v_cvt_pk_bf16_f32 v0, v0, v1
	v_mul_f32_e32 v1, v28, v11
	v_mul_f32_e32 v1, v1, v2
	v_mul_f32_e32 v2, v10, v11
	v_mul_f32_e32 v2, v2, v3
	v_cvt_pk_bf16_f32 v1, v1, v2
	global_store_dwordx2 v[8:9], v[0:1], off offset:224
	global_load_dwordx4 v[0:3], v[192:193], off offset:480
	s_waitcnt vmcnt(0)
	v_mul_f32_e32 v0, v6, v0
	v_mul_f32_e32 v6, v7, v11
	v_mul_f32_e32 v1, v6, v1
	v_cvt_pk_bf16_f32 v0, v0, v1
	v_mul_f32_e32 v1, v4, v11
	v_mul_f32_e32 v1, v1, v2
	v_mul_f32_e32 v2, v5, v11
	v_mul_f32_e32 v2, v2, v3
	v_cvt_pk_bf16_f32 v1, v1, v2
	global_store_dwordx2 v[8:9], v[0:1], off offset:240
	s_branch .LBB0_296

; #define AT_LOADK(t) do { kr0 = *(const v4u*)(kg + (size_t)(t) * 64 * 1024); kr1 = *(const v4u*)(kg + (size_t)(t) * 64 * 1024 + 32 * 1024); } while (0)
; #define AT_LOADV(t) do { vr0 = *(const v4u*)(vg + (t) * 64); vr1 = *(const v4u*)(vg + (size_t)64 * SEQ + (t) * 64); } while (0)
; #define AT_STOREK(bf) do { *(LAS v4u*)(lds + (bf) * AT_KBUF + kso) = kr0; *(LAS v4u*)(lds + (bf) * AT_KBUF + kso + 32 * AT_KSTR * 2) = kr1; } while (0)
; #define AT_STOREV(bf) do { *(LAS v2u*)(lds + (bf) * AT_VBUF + vso) = (v2u){vr0.x, vr0.y}; *(LAS v2u*)(lds + (bf) * AT_VBUF + vso + 8) = (v2u){vr0.z, vr0.w}; \
;         *(LAS v2u*)(lds + (bf) * AT_VBUF + vso + 64 * AT_VSTR * 2) = (v2u){vr1.x, vr1.y}; *(LAS v2u*)(lds + (bf) * AT_VBUF + vso + 64 * AT_VSTR * 2 + 8) = (v2u){vr1.z, vr1.w}; } while (0)
;     ...
;             if (t < NTw) AT_QKB(t & 1);
;             if (!(AMODE & 4) && t >= 1) { if (t + 1 < NT) AT_STOREK((t + 1) & 1); if (t < NT) AT_STOREV(t & 1); }
;             __syncthreads();
;             if (!(AMODE & 4)) { if (t + 2 < NT) AT_LOADK(t + 2); if (t + 1 < NT) AT_LOADV(t + 1); }
;             if (t < NTw) {
;                 AT_SOFTMAX(t);
;                 __syncthreads();
;                 AT_PVB(t & 1);
;             } else __syncthreads();
.LBB0_315:
	s_cmp_eq_u32 s4, 0
	s_barrier
	s_setprio 1
	s_cbranch_scc1 .LBB0_317
	global_load_dwordx4 v[160:163], v[204:205], off
	global_load_dwordx4 v[164:167], v[206:207], off
.LBB0_317:
	global_load_dwordx4 v[168:171], v[178:179], off offset:128
	global_load_dwordx4 v[172:175], v[208:209], off
	s_mov_b64 s[40:41], -1
	s_andn2_b64 vcc, exec, s[6:7]
	s_mov_b64 s[6:7], -1
	s_cbranch_vccnz .LBB0_319
	s_mov_b64 s[6:7], 0
	s_setprio 0
	s_barrier

;     ...
;                 __syncthreads();
;                 AT_PVB(t & 1);
.LBB0_386:
	v_max3_f32 v33, v16, v17, v0
	v_max3_f32 v34, v18, v19, v1
	s_cmp_eq_u64 exec, 0
	v_max3_f32 v33, v33, v2, v3
	v_max3_f32 v34, v34, v22, v23
	s_cselect_b64 s[40:41], -1, 0
	v_max3_f32 v33, v33, v20, v21
	v_max3_f32 v34, v34, v6, v7
	v_add_u32_e32 v46, 0x9800, v223
	v_max3_f32 v33, v33, v4, v5
	v_max3_f32 v34, v34, v26, v27
	s_nop 0
	v_max3_f32 v33, v33, v24, v25
	v_max3_f32 v34, v34, v10, v11
	s_nop 0
	v_max3_f32 v33, v33, v8, v9
	v_max3_f32 v34, v34, v30, v31
	s_nop 0
	v_max3_f32 v33, v33, v28, v29
	v_max3_f32 v34, v34, v14, v15
	s_nop 0
	v_max3_f32 v33, v33, v12, v13
	v_max_f32_e32 v34, v34, v34
	v_max_f32_e32 v33, v33, v33
	v_max_f32_e32 v33, v33, v34
	v_mov_b32_e32 v34, v33
	s_nop 1
	v_permlane32_swap_b32_e32 v33, v34
	v_max_f32_e32 v34, v34, v34
	v_max_f32_e32 v33, v33, v33
	v_max_f32_e32 v33, v33, v34
	v_add_f32_e32 v33, 0, v33
	v_cndmask_b32_e64 v214, v33, 0, s[40:41]
	v_sub_f32_e32 v16, v16, v214
	v_sub_f32_e32 v17, v17, v214
	v_sub_f32_e32 v0, v0, v214
	v_sub_f32_e32 v1, v1, v214
	v_exp_f32_e32 v16, v16
	v_exp_f32_e32 v17, v17
	v_exp_f32_e32 v38, v0
	v_exp_f32_e32 v39, v1
	v_sub_f32_e32 v18, v18, v214
	v_sub_f32_e32 v19, v19, v214
	v_sub_f32_e32 v2, v2, v214
	v_sub_f32_e32 v3, v3, v214
	v_exp_f32_e32 v18, v18
	v_exp_f32_e32 v19, v19
	v_exp_f32_e32 v40, v2
	v_exp_f32_e32 v41, v3
	v_sub_f32_e32 v2, v20, v214
	v_sub_f32_e32 v3, v21, v214
	v_add_f32_e32 v0, 0, v16
	v_add_f32_e32 v1, 0, v17
	v_sub_f32_e32 v4, v4, v214
	v_sub_f32_e32 v5, v5, v214
	v_exp_f32_e32 v2, v2
	v_exp_f32_e32 v3, v3
	v_add_f32_e32 v0, v38, v0
	v_add_f32_e32 v1, v39, v1
	v_exp_f32_e32 v4, v4
	v_exp_f32_e32 v5, v5
	v_sub_f32_e32 v20, v22, v214
	v_sub_f32_e32 v21, v23, v214
	v_add_f32_e32 v0, v18, v0
	v_add_f32_e32 v1, v19, v1
	v_sub_f32_e32 v6, v6, v214
	v_sub_f32_e32 v7, v7, v214
	v_exp_f32_e32 v20, v20
	v_exp_f32_e32 v21, v21
	v_add_f32_e32 v0, v40, v0
	v_add_f32_e32 v1, v41, v1
	v_exp_f32_e32 v6, v6
	v_exp_f32_e32 v7, v7
	v_sub_f32_e32 v22, v24, v214
	v_sub_f32_e32 v23, v25, v214
	v_add_f32_e32 v0, v2, v0
	v_add_f32_e32 v1, v3, v1
	v_sub_f32_e32 v8, v8, v214
	v_sub_f32_e32 v9, v9, v214
	v_exp_f32_e32 v22, v22
	v_exp_f32_e32 v23, v23
	v_add_f32_e32 v0, v4, v0
	v_add_f32_e32 v1, v5, v1
	v_exp_f32_e32 v8, v8
	v_exp_f32_e32 v9, v9
	v_sub_f32_e32 v24, v26, v214
	v_sub_f32_e32 v25, v27, v214
	v_add_f32_e32 v0, v20, v0
	v_add_f32_e32 v1, v21, v1
	v_sub_f32_e32 v10, v10, v214
	v_sub_f32_e32 v11, v11, v214
	v_exp_f32_e32 v24, v24
	v_exp_f32_e32 v25, v25
	v_add_f32_e32 v0, v6, v0
	v_add_f32_e32 v1, v7, v1
	v_exp_f32_e32 v10, v10
	v_exp_f32_e32 v11, v11
	v_sub_f32_e32 v26, v28, v214
	v_sub_f32_e32 v27, v29, v214
	v_add_f32_e32 v0, v22, v0
	v_add_f32_e32 v1, v23, v1
	v_sub_f32_e32 v12, v12, v214
	v_sub_f32_e32 v13, v13, v214
	v_exp_f32_e32 v26, v26
	v_exp_f32_e32 v27, v27
	v_add_f32_e32 v0, v8, v0
	v_add_f32_e32 v1, v9, v1
	v_exp_f32_e32 v12, v12
	v_exp_f32_e32 v13, v13
	v_add_f32_e32 v0, v24, v0
	v_add_f32_e32 v1, v25, v1
	v_sub_f32_e32 v14, v14, v214
	v_sub_f32_e32 v15, v15, v214
	v_add_f32_e32 v0, v10, v0
	v_add_f32_e32 v1, v11, v1
	v_exp_f32_e32 v14, v14
	v_add_f32_e32 v0, v26, v0
	v_add_f32_e32 v1, v27, v1
	v_exp_f32_e32 v15, v15
	v_add_f32_e32 v28, v12, v0
	v_add_f32_e32 v29, v13, v1
	v_sub_f32_e32 v0, v30, v214
	v_sub_f32_e32 v1, v31, v214
	v_add_u32_e32 v33, 0x8800, v223
	v_exp_f32_e32 v30, v0
	v_exp_f32_e32 v31, v1
	v_cvt_pk_bf16_f32 v0, v16, v17
	v_cvt_pk_bf16_f32 v1, v18, v19
	v_cvt_pk_bf16_f32 v2, v2, v3
	v_cvt_pk_bf16_f32 v3, v20, v21
	v_cvt_pk_bf16_f32 v34, v22, v23
	v_cvt_pk_bf16_f32 v35, v24, v25
	v_cvt_pk_bf16_f32 v36, v26, v27
	v_cvt_pk_bf16_f32 v37, v30, v31
	v_cvt_pk_bf16_f32 v38, v38, v39
	v_cvt_pk_bf16_f32 v39, v40, v41
	v_cvt_pk_bf16_f32 v40, v4, v5
	v_cvt_pk_bf16_f32 v41, v6, v7
	v_cvt_pk_bf16_f32 v42, v8, v9
	v_cvt_pk_bf16_f32 v43, v10, v11
	v_cvt_pk_bf16_f32 v44, v12, v13
	v_cvt_pk_bf16_f32 v45, v14, v15
	s_setprio 0
	s_barrier
	ds_read2_b64 v[4:7], v33 offset1:2
	ds_read2_b64 v[8:11], v46 offset0:32 offset1:34
	v_add_f32_e32 v12, v30, v28
	v_add_f32_e32 v13, v31, v29
	s_nop 0
	v_add_f32_e32 v12, v14, v12
	v_add_f32_e32 v13, v15, v13
	s_nop 0
	v_add_f32_e32 v12, v12, v13
	v_add_f32_e32 v250, 0, v12
	v_add_u32_e32 v47, 0xa800, v223
	ds_read2_b64 v[12:15], v47 offset0:64 offset1:66
	v_add_u32_e32 v104, 0xb800, v223
	ds_read2_b64 v[80:83], v104 offset0:96 offset1:98
	ds_read2_b64 v[84:87], v33 offset0:4 offset1:6
	ds_read2_b64 v[88:91], v46 offset0:36 offset1:38
	s_waitcnt lgkmcnt(5)
	v_mfma_f32_32x32x16_bf16 v[64:79], v[4:7], v[0:3], 0
	s_waitcnt lgkmcnt(4)
	v_mfma_f32_32x32x16_bf16 v[48:63], v[8:11], v[0:3], 0
	ds_read2_b64 v[92:95], v47 offset0:68 offset1:70
	ds_read2_b64 v[96:99], v104 offset0:100 offset1:102
	s_waitcnt lgkmcnt(5)
	v_mfma_f32_32x32x16_bf16 v[16:31], v[12:15], v[0:3], 0
	s_waitcnt lgkmcnt(4)
	v_mfma_f32_32x32x16_bf16 v[0:15], v[80:83], v[0:3], 0
	ds_read2_b64 v[80:83], v33 offset0:8 offset1:10
	ds_read2_b64 v[100:103], v46 offset0:40 offset1:42
	s_waitcnt lgkmcnt(5)
	v_mfma_f32_32x32x16_bf16 v[64:79], v[84:87], v[34:37], v[64:79]
	s_waitcnt lgkmcnt(4)
	v_mfma_f32_32x32x16_bf16 v[48:63], v[88:91], v[34:37], v[48:63]
	ds_read2_b64 v[84:87], v47 offset0:72 offset1:74
	ds_read2_b64 v[88:91], v104 offset0:104 offset1:106
	s_waitcnt lgkmcnt(5)
	v_mfma_f32_32x32x16_bf16 v[16:31], v[92:95], v[34:37], v[16:31]
	s_waitcnt lgkmcnt(4)
	v_mfma_f32_32x32x16_bf16 v[0:15], v[96:99], v[34:37], v[0:15]
	ds_read2_b64 v[34:37], v33 offset0:12 offset1:14
	ds_read2_b64 v[92:95], v46 offset0:44 offset1:46
	s_waitcnt lgkmcnt(5)
	v_mfma_f32_32x32x16_bf16 v[64:79], v[80:83], v[38:41], v[64:79]
	s_waitcnt lgkmcnt(4)
	v_mfma_f32_32x32x16_bf16 v[48:63], v[100:103], v[38:41], v[48:63]
	ds_read2_b64 v[80:83], v47 offset0:76 offset1:78
	ds_read2_b64 v[96:99], v104 offset0:108 offset1:110
	s_waitcnt lgkmcnt(5)
	v_mfma_f32_32x32x16_bf16 v[16:31], v[84:87], v[38:41], v[16:31]
	s_waitcnt lgkmcnt(4)
	v_mfma_f32_32x32x16_bf16 v[0:15], v[88:91], v[38:41], v[0:15]
	s_waitcnt lgkmcnt(3)
	v_mfma_f32_32x32x16_bf16 v[64:79], v[34:37], v[42:45], v[64:79]
	s_waitcnt lgkmcnt(2)
	v_mfma_f32_32x32x16_bf16 v[48:63], v[92:95], v[42:45], v[48:63]
	s_waitcnt lgkmcnt(1)
	v_mfma_f32_32x32x16_bf16 v[16:31], v[80:83], v[42:45], v[16:31]
	s_waitcnt lgkmcnt(0)
	v_mfma_f32_32x32x16_bf16 v[0:15], v[96:99], v[42:45], v[0:15]
	s_branch .LBB0_388

;     ...
;             if (t < NTw) AT_QKB(t & 1);
.LBB0_389:
	s_bitcmp1_b32 s50, 0
	s_cselect_b32 s34, 0x4400, 0
	v_add_u32_e32 v33, s34, v221
	ds_read_b128 v[34:37], v33
	ds_read_b128 v[38:41], v33 offset:8704
	ds_read_b128 v[42:45], v33 offset:32
	ds_read_b128 v[112:115], v33 offset:8736
	ds_read_b128 v[116:119], v33 offset:64
	ds_read_b128 v[120:123], v33 offset:8768
	s_waitcnt lgkmcnt(5)
	v_mfma_f32_32x32x16_bf16 v[96:111], v[34:37], v[144:147], 0
	s_waitcnt lgkmcnt(4)
	v_mfma_f32_32x32x16_bf16 v[80:95], v[38:41], v[144:147], 0
	ds_read_b128 v[34:37], v33 offset:96
	ds_read_b128 v[38:41], v33 offset:8800
	s_waitcnt lgkmcnt(5)
	v_mfma_f32_32x32x16_bf16 v[96:111], v[42:45], v[148:151], v[96:111]
	s_waitcnt lgkmcnt(4)
	v_mfma_f32_32x32x16_bf16 v[80:95], v[112:115], v[148:151], v[80:95]
	s_waitcnt lgkmcnt(3)
	v_mfma_f32_32x32x16_bf16 v[96:111], v[116:119], v[152:155], v[96:111]
	s_waitcnt lgkmcnt(2)
	v_mfma_f32_32x32x16_bf16 v[80:95], v[120:123], v[152:155], v[80:95]
	s_waitcnt lgkmcnt(1)
	v_mfma_f32_32x32x16_bf16 v[96:111], v[34:37], v[156:159], v[96:111]
	s_waitcnt lgkmcnt(0)
	v_mfma_f32_32x32x16_bf16 v[80:95], v[38:41], v[156:159], v[80:95]
	s_branch .LBB0_391

; #define AT_LOADK(t) do { kr0 = *(const v4u*)(kg + (size_t)(t) * 64 * 1024); kr1 = *(const v4u*)(kg + (size_t)(t) * 64 * 1024 + 32 * 1024); } while (0)
; #define AT_LOADV(t) do { vr0 = *(const v4u*)(vg + (t) * 64); vr1 = *(const v4u*)(vg + (size_t)64 * SEQ + (t) * 64); } while (0)
; #define AT_STOREK(bf) do { *(LAS v4u*)(lds + (bf) * AT_KBUF + kso) = kr0; *(LAS v4u*)(lds + (bf) * AT_KBUF + kso + 32 * AT_KSTR * 2) = kr1; } while (0)
; #define AT_STOREV(bf) do { *(LAS v2u*)(lds + (bf) * AT_VBUF + vso) = (v2u){vr0.x, vr0.y}; *(LAS v2u*)(lds + (bf) * AT_VBUF + vso + 8) = (v2u){vr0.z, vr0.w}; \
;         *(LAS v2u*)(lds + (bf) * AT_VBUF + vso + 64 * AT_VSTR * 2) = (v2u){vr1.x, vr1.y}; *(LAS v2u*)(lds + (bf) * AT_VBUF + vso + 64 * AT_VSTR * 2 + 8) = (v2u){vr1.z, vr1.w}; } while (0)
;     ...
;             if (!(AMODE & 4) && t >= 1) { if (t + 1 < NT) AT_STOREK((t + 1) & 1); if (t < NT) AT_STOREV(t & 1); }
;             __syncthreads();
;             if (!(AMODE & 4)) { if (t + 2 < NT) AT_LOADK(t + 2); if (t + 1 < NT) AT_LOADV(t + 1); }
.LBB0_393:
	s_bitcmp1_b32 s50, 0
	s_cselect_b32 s49, 0x4400, 0
	v_add_u32_e32 v33, s49, v220
	v_add_u32_e32 v34, 0x8800, v33
	v_add_u32_e32 v33, 0xaa00, v33
	s_cmp_ge_i32 s50, s4
	s_waitcnt vmcnt(1)
	ds_write2_b64 v34, v[168:169], v[170:171] offset1:1
	s_waitcnt vmcnt(0)
	ds_write2_b64 v33, v[172:173], v[174:175] offset1:1
	s_waitcnt lgkmcnt(0)
	s_barrier
	s_setprio 1
	s_cbranch_scc0 .LBB0_397
	s_andn2_b64 vcc, exec, s[34:35]
	s_cbranch_vccz .LBB0_398

;     ...
;             } else __syncthreads();
.LBB0_399:
	s_setprio 0
	s_barrier
	s_cbranch_execnz .LBB0_469
.LBB0_400:
	s_add_i32 s6, s42, s19
	s_cmpk_gt_i32 s6, 0xaf
	s_cbranch_scc1 .LBB0_466
	v_add_u32_e32 v33, s42, v251
	s_mov_b32 s50, 0x11000
	s_mov_b32 s51, 0x10f80
	v_mov_b32_e32 v47, 0xf149f2ca
	v_add_u32_e32 v34, 0xffffffc0, v33
	v_min_u32_e32 v36, 0x7f, v34
	v_min_u32_e32 v37, 0x9f, v34
	v_lshl_add_u32 v36, v36, 2, s50
	v_lshl_add_u32 v37, v37, 2, s51
	ds_read_b32 v112, v36
	ds_read_b32 v128, v37
	v_add_u32_e32 v34, 0xffffffbf, v33
	v_min_u32_e32 v38, 0x7f, v34
	v_min_u32_e32 v39, 0x9f, v34
	v_lshl_add_u32 v38, v38, 2, s50
	v_lshl_add_u32 v39, v39, 2, s51
	ds_read_b32 v113, v38
	ds_read_b32 v129, v39
	v_add_u32_e32 v34, 0xffffffbe, v33
	v_min_u32_e32 v40, 0x7f, v34
	v_min_u32_e32 v41, 0x9f, v34
	v_lshl_add_u32 v40, v40, 2, s50
	v_lshl_add_u32 v41, v41, 2, s51
	ds_read_b32 v114, v40
	ds_read_b32 v130, v41
	v_add_u32_e32 v34, 0xffffffbd, v33
	v_min_u32_e32 v42, 0x7f, v34
	v_min_u32_e32 v43, 0x9f, v34
	v_lshl_add_u32 v42, v42, 2, s50
	v_lshl_add_u32 v43, v43, 2, s51
	ds_read_b32 v115, v42
	ds_read_b32 v131, v43
	v_add_u32_e32 v34, 0xffffffb8, v33
	v_min_u32_e32 v36, 0x7f, v34
	v_min_u32_e32 v37, 0x9f, v34
	v_lshl_add_u32 v36, v36, 2, s50
	v_lshl_add_u32 v37, v37, 2, s51
	ds_read_b32 v116, v36
	ds_read_b32 v132, v37
	v_add_u32_e32 v34, 0xffffffb7, v33
	v_min_u32_e32 v38, 0x7f, v34
	v_min_u32_e32 v39, 0x9f, v34
	v_lshl_add_u32 v38, v38, 2, s50
	v_lshl_add_u32 v39, v39, 2, s51
	ds_read_b32 v117, v38
	ds_read_b32 v133, v39
	s_waitcnt lgkmcnt(0)
	v_add_u32_e32 v34, 0xffffffb6, v33
	v_min_u32_e32 v40, 0x7f, v34
	v_min_u32_e32 v41, 0x9f, v34
	v_lshl_add_u32 v40, v40, 2, s50
	v_lshl_add_u32 v41, v41, 2, s51
	ds_read_b32 v118, v40
	ds_read_b32 v134, v41
	v_add_u32_e32 v34, 0xffffffb5, v33
	v_min_u32_e32 v42, 0x7f, v34
	v_min_u32_e32 v43, 0x9f, v34
	v_lshl_add_u32 v42, v42, 2, s50
	v_lshl_add_u32 v43, v43, 2, s51
	ds_read_b32 v119, v42
	ds_read_b32 v135, v43
	v_add_u32_e32 v34, 0xffffffb0, v33
	v_min_u32_e32 v36, 0x7f, v34
	v_min_u32_e32 v37, 0x9f, v34
	v_lshl_add_u32 v36, v36, 2, s50
	v_lshl_add_u32 v37, v37, 2, s51
	ds_read_b32 v120, v36
	ds_read_b32 v136, v37
	v_add_u32_e32 v34, 0xffffffaf, v33
	v_min_u32_e32 v38, 0x7f, v34
	v_min_u32_e32 v39, 0x9f, v34
	v_lshl_add_u32 v38, v38, 2, s50
	v_lshl_add_u32 v39, v39, 2, s51
	ds_read_b32 v121, v38
	ds_read_b32 v137, v39
	v_add_u32_e32 v34, 0xffffffae, v33
	v_min_u32_e32 v40, 0x7f, v34
	v_min_u32_e32 v41, 0x9f, v34
	v_lshl_add_u32 v40, v40, 2, s50
	v_lshl_add_u32 v41, v41, 2, s51
	ds_read_b32 v122, v40
	ds_read_b32 v138, v41
	v_add_u32_e32 v34, 0xffffffad, v33
	v_min_u32_e32 v42, 0x7f, v34
	v_min_u32_e32 v43, 0x9f, v34
	v_lshl_add_u32 v42, v42, 2, s50
	v_lshl_add_u32 v43, v43, 2, s51
	ds_read_b32 v123, v42
	ds_read_b32 v139, v43
	v_add_u32_e32 v34, 0xffffffc0, v33
	v_cmp_lt_i32_e64 s[6:7], -1, v34
	v_cmp_lt_i32_e64 s[60:61], 31, v34
	v_add_f32_e32 v112, v96, v112
	v_add_f32_e32 v128, v80, v128
	v_cndmask_b32_e64 v96, v47, v112, s[6:7]
	v_cndmask_b32_e64 v80, v47, v128, s[60:61]
	v_add_u32_e32 v34, 0xffffffbf, v33
	v_cmp_lt_i32_e64 s[6:7], -1, v34
	v_cmp_lt_i32_e64 s[60:61], 31, v34
	v_add_f32_e32 v113, v97, v113
	v_add_f32_e32 v129, v81, v129
	v_cndmask_b32_e64 v97, v47, v113, s[6:7]
	v_cndmask_b32_e64 v81, v47, v129, s[60:61]
	v_add_u32_e32 v34, 0xffffffbe, v33
	v_cmp_lt_i32_e64 s[6:7], -1, v34
	v_cmp_lt_i32_e64 s[60:61], 31, v34
	v_add_f32_e32 v114, v98, v114
	v_add_f32_e32 v130, v82, v130
	v_cndmask_b32_e64 v98, v47, v114, s[6:7]
	v_cndmask_b32_e64 v82, v47, v130, s[60:61]
	v_add_u32_e32 v34, 0xffffffbd, v33
	v_cmp_lt_i32_e64 s[6:7], -1, v34
	v_cmp_lt_i32_e64 s[60:61], 31, v34
	v_add_f32_e32 v115, v99, v115
	v_add_f32_e32 v131, v83, v131
	v_cndmask_b32_e64 v99, v47, v115, s[6:7]
	v_cndmask_b32_e64 v83, v47, v131, s[60:61]
	v_add_u32_e32 v34, 0xffffffb8, v33
	v_cmp_lt_i32_e64 s[6:7], -1, v34
	v_cmp_lt_i32_e64 s[60:61], 31, v34
	v_add_f32_e32 v116, v100, v116
	v_add_f32_e32 v132, v84, v132
	v_cndmask_b32_e64 v100, v47, v116, s[6:7]
	v_cndmask_b32_e64 v84, v47, v132, s[60:61]
	v_add_u32_e32 v34, 0xffffffb7, v33
	v_cmp_lt_i32_e64 s[6:7], -1, v34
	v_cmp_lt_i32_e64 s[60:61], 31, v34
	v_add_f32_e32 v117, v101, v117
	v_add_f32_e32 v133, v85, v133
	v_cndmask_b32_e64 v101, v47, v117, s[6:7]
	v_cndmask_b32_e64 v85, v47, v133, s[60:61]
	s_waitcnt lgkmcnt(0)
	v_add_u32_e32 v34, 0xffffffa8, v33
	v_min_u32_e32 v36, 0x7f, v34
	v_min_u32_e32 v37, 0x9f, v34
	v_lshl_add_u32 v36, v36, 2, s50
	v_lshl_add_u32 v37, v37, 2, s51
	ds_read_b32 v124, v36
	ds_read_b32 v140, v37
	v_add_u32_e32 v34, 0xffffffa7, v33
	v_min_u32_e32 v38, 0x7f, v34
	v_min_u32_e32 v39, 0x9f, v34
	v_lshl_add_u32 v38, v38, 2, s50
	v_lshl_add_u32 v39, v39, 2, s51
	ds_read_b32 v125, v38
	ds_read_b32 v141, v39
	v_add_u32_e32 v34, 0xffffffa6, v33
	v_min_u32_e32 v40, 0x7f, v34
	v_min_u32_e32 v41, 0x9f, v34
	v_lshl_add_u32 v40, v40, 2, s50
	v_lshl_add_u32 v41, v41, 2, s51
	ds_read_b32 v126, v40
	ds_read_b32 v142, v41
	v_add_u32_e32 v34, 0xffffffa5, v33
	v_min_u32_e32 v42, 0x7f, v34
	v_min_u32_e32 v43, 0x9f, v34
	v_lshl_add_u32 v42, v42, 2, s50
	v_lshl_add_u32 v43, v43, 2, s51
	ds_read_b32 v127, v42
	ds_read_b32 v143, v43
	v_add_u32_e32 v34, 0xffffffb6, v33
	v_cmp_lt_i32_e64 s[6:7], -1, v34
	v_cmp_lt_i32_e64 s[60:61], 31, v34
	v_add_f32_e32 v118, v102, v118
	v_add_f32_e32 v134, v86, v134
	v_cndmask_b32_e64 v102, v47, v118, s[6:7]
	v_cndmask_b32_e64 v86, v47, v134, s[60:61]
	v_add_u32_e32 v34, 0xffffffb5, v33
	v_cmp_lt_i32_e64 s[6:7], -1, v34
	v_cmp_lt_i32_e64 s[60:61], 31, v34
	v_add_f32_e32 v119, v103, v119
	v_add_f32_e32 v135, v87, v135
	v_cndmask_b32_e64 v103, v47, v119, s[6:7]
	v_cndmask_b32_e64 v87, v47, v135, s[60:61]
	v_add_u32_e32 v34, 0xffffffb0, v33
	v_cmp_lt_i32_e64 s[6:7], -1, v34
	v_cmp_lt_i32_e64 s[60:61], 31, v34
	v_add_f32_e32 v120, v104, v120
	v_add_f32_e32 v136, v88, v136
	v_cndmask_b32_e64 v104, v47, v120, s[6:7]
	v_cndmask_b32_e64 v88, v47, v136, s[60:61]
	v_add_u32_e32 v34, 0xffffffaf, v33
	v_cmp_lt_i32_e64 s[6:7], -1, v34
	v_cmp_lt_i32_e64 s[60:61], 31, v34
	v_add_f32_e32 v121, v105, v121
	v_add_f32_e32 v137, v89, v137
	v_cndmask_b32_e64 v105, v47, v121, s[6:7]
	v_cndmask_b32_e64 v89, v47, v137, s[60:61]
	v_add_u32_e32 v34, 0xffffffae, v33
	v_cmp_lt_i32_e64 s[6:7], -1, v34
	v_cmp_lt_i32_e64 s[60:61], 31, v34
	v_add_f32_e32 v122, v106, v122
	v_add_f32_e32 v138, v90, v138
	v_cndmask_b32_e64 v106, v47, v122, s[6:7]
	v_cndmask_b32_e64 v90, v47, v138, s[60:61]
	v_add_u32_e32 v34, 0xffffffad, v33
	v_cmp_lt_i32_e64 s[6:7], -1, v34
	v_cmp_lt_i32_e64 s[60:61], 31, v34
	v_add_f32_e32 v123, v107, v123
	v_add_f32_e32 v139, v91, v139
	v_cndmask_b32_e64 v107, v47, v123, s[6:7]
	v_cndmask_b32_e64 v91, v47, v139, s[60:61]
	s_waitcnt lgkmcnt(0)
	v_add_u32_e32 v34, 0xffffffa8, v33
	v_cmp_lt_i32_e64 s[6:7], -1, v34
	v_cmp_lt_i32_e64 s[60:61], 31, v34
	v_add_f32_e32 v124, v108, v124
	v_add_f32_e32 v140, v92, v140
	v_cndmask_b32_e64 v108, v47, v124, s[6:7]
	v_cndmask_b32_e64 v92, v47, v140, s[60:61]
	v_add_u32_e32 v34, 0xffffffa7, v33
	v_cmp_lt_i32_e64 s[6:7], -1, v34
	v_cmp_lt_i32_e64 s[60:61], 31, v34
	v_add_f32_e32 v125, v109, v125
	v_add_f32_e32 v141, v93, v141
	v_cndmask_b32_e64 v109, v47, v125, s[6:7]
	v_cndmask_b32_e64 v93, v47, v141, s[60:61]
	v_add_u32_e32 v34, 0xffffffa6, v33
	v_cmp_lt_i32_e64 s[6:7], -1, v34
	v_cmp_lt_i32_e64 s[60:61], 31, v34
	v_add_f32_e32 v126, v110, v126
	v_add_f32_e32 v142, v94, v142
	v_cndmask_b32_e64 v110, v47, v126, s[6:7]
	v_cndmask_b32_e64 v94, v47, v142, s[60:61]
	v_add_u32_e32 v34, 0xffffffa5, v33
	v_cmp_lt_i32_e64 s[6:7], -1, v34
	v_cmp_lt_i32_e64 s[60:61], 31, v34
	v_add_f32_e32 v127, v111, v127
	v_add_f32_e32 v143, v95, v143
	v_cndmask_b32_e64 v111, v47, v127, s[6:7]
	v_cndmask_b32_e64 v95, v47, v143, s[60:61]

.LBB0_468:
	v_sub_f32_e32 v34, v96, v214
	v_sub_f32_e32 v35, v97, v214
	v_sub_f32_e32 v36, v80, v214
	v_sub_f32_e32 v37, v81, v214
	v_exp_f32_e32 v34, v34
	v_exp_f32_e32 v35, v35
	v_exp_f32_e32 v42, v36
	v_exp_f32_e32 v43, v37
	v_sub_f32_e32 v38, v98, v214
	v_sub_f32_e32 v39, v99, v214
	v_sub_f32_e32 v40, v82, v214
	v_sub_f32_e32 v41, v83, v214
	v_exp_f32_e32 v38, v38
	v_exp_f32_e32 v39, v39
	v_exp_f32_e32 v44, v40
	v_exp_f32_e32 v45, v41
	v_sub_f32_e32 v40, v100, v214
	v_sub_f32_e32 v41, v101, v214
	v_add_f32_e32 v36, 0, v34
	v_add_f32_e32 v37, 0, v35
	v_sub_f32_e32 v46, v84, v214
	v_sub_f32_e32 v47, v85, v214
	v_exp_f32_e32 v40, v40
	v_exp_f32_e32 v41, v41
	v_add_f32_e32 v36, v42, v36
	v_add_f32_e32 v37, v43, v37
	v_exp_f32_e32 v46, v46
	v_exp_f32_e32 v47, v47
	v_sub_f32_e32 v80, v102, v214
	v_sub_f32_e32 v81, v103, v214
	v_add_f32_e32 v36, v38, v36
	v_add_f32_e32 v37, v39, v37
	v_sub_f32_e32 v82, v86, v214
	v_sub_f32_e32 v83, v87, v214
	v_exp_f32_e32 v80, v80
	v_exp_f32_e32 v81, v81
	v_add_f32_e32 v36, v44, v36
	v_add_f32_e32 v37, v45, v37
	v_exp_f32_e32 v82, v82
	v_exp_f32_e32 v83, v83
	v_sub_f32_e32 v84, v104, v214
	v_sub_f32_e32 v85, v105, v214
	v_add_f32_e32 v36, v40, v36
	v_add_f32_e32 v37, v41, v37
	v_sub_f32_e32 v86, v88, v214
	v_sub_f32_e32 v87, v89, v214
	v_exp_f32_e32 v84, v84
	v_exp_f32_e32 v85, v85
	v_add_f32_e32 v36, v46, v36
	v_add_f32_e32 v37, v47, v37
	v_exp_f32_e32 v86, v86
	v_exp_f32_e32 v87, v87
	v_sub_f32_e32 v88, v106, v214
	v_sub_f32_e32 v89, v107, v214
	v_add_f32_e32 v36, v80, v36
	v_add_f32_e32 v37, v81, v37
	v_sub_f32_e32 v90, v90, v214
	v_sub_f32_e32 v91, v91, v214
	v_exp_f32_e32 v88, v88
	v_exp_f32_e32 v89, v89
	v_add_f32_e32 v36, v82, v36
	v_add_f32_e32 v37, v83, v37
	v_exp_f32_e32 v90, v90
	v_exp_f32_e32 v91, v91
	v_sub_f32_e32 v96, v108, v214
	v_sub_f32_e32 v97, v109, v214
	v_add_f32_e32 v36, v84, v36
	v_add_f32_e32 v37, v85, v37
	v_sub_f32_e32 v92, v92, v214
	v_sub_f32_e32 v93, v93, v214
	v_exp_f32_e32 v96, v96
	v_exp_f32_e32 v97, v97
	v_add_f32_e32 v36, v86, v36
	v_add_f32_e32 v37, v87, v37
	v_exp_f32_e32 v92, v92
	v_exp_f32_e32 v93, v93
	v_add_f32_e32 v36, v88, v36
	v_add_f32_e32 v37, v89, v37
	v_sub_f32_e32 v94, v94, v214
	v_sub_f32_e32 v95, v95, v214
	v_add_f32_e32 v36, v90, v36
	v_add_f32_e32 v37, v91, v37
	v_exp_f32_e32 v94, v94
	v_add_f32_e32 v36, v96, v36
	v_add_f32_e32 v37, v97, v37
	v_exp_f32_e32 v95, v95
	v_add_f32_e32 v98, v92, v36
	v_add_f32_e32 v99, v93, v37
	v_sub_f32_e32 v36, v110, v214
	v_sub_f32_e32 v37, v111, v214
	v_add_u32_e32 v33, s49, v223
	v_exp_f32_e32 v100, v36
	v_exp_f32_e32 v101, v37
	v_add_u32_e32 v108, 0x8800, v33
	v_add_u32_e32 v109, 0x9800, v33
	v_cvt_pk_bf16_f32 v34, v34, v35
	v_cvt_pk_bf16_f32 v35, v38, v39
	v_cvt_pk_bf16_f32 v36, v40, v41
	v_cvt_pk_bf16_f32 v37, v80, v81
	v_cvt_pk_bf16_f32 v38, v84, v85
	v_cvt_pk_bf16_f32 v39, v88, v89
	v_cvt_pk_bf16_f32 v40, v96, v97
	v_cvt_pk_bf16_f32 v41, v100, v101
	v_cvt_pk_bf16_f32 v42, v42, v43
	v_cvt_pk_bf16_f32 v43, v44, v45
	v_cvt_pk_bf16_f32 v44, v46, v47
	v_cvt_pk_bf16_f32 v45, v82, v83
	v_cvt_pk_bf16_f32 v80, v86, v87
	v_cvt_pk_bf16_f32 v81, v90, v91
	v_cvt_pk_bf16_f32 v82, v92, v93
	v_cvt_pk_bf16_f32 v83, v94, v95
	s_setprio 0
	s_barrier
	ds_read2_b64 v[84:87], v108 offset1:2
	ds_read2_b64 v[88:91], v109 offset0:32 offset1:34
	v_add_f32_e32 v46, v100, v98
	v_add_f32_e32 v47, v101, v99
	s_nop 0
	v_add_f32_e32 v46, v94, v46
	v_add_f32_e32 v47, v95, v47
	s_nop 0
	v_add_f32_e32 v46, v46, v47
	v_add_f32_e32 v250, v250, v46
	v_add_u32_e32 v46, 0xa800, v33
	v_add_u32_e32 v33, 0xb800, v33
	ds_read2_b64 v[92:95], v46 offset0:64 offset1:66
	ds_read2_b64 v[96:99], v33 offset0:96 offset1:98
	ds_read2_b64 v[100:103], v108 offset0:4 offset1:6
	ds_read2_b64 v[104:107], v109 offset0:36 offset1:38
	s_waitcnt lgkmcnt(5)
	v_mfma_f32_32x32x16_bf16 v[64:79], v[84:87], v[34:37], v[64:79]
	s_waitcnt lgkmcnt(4)
	v_mfma_f32_32x32x16_bf16 v[48:63], v[88:91], v[34:37], v[48:63]
	ds_read2_b64 v[84:87], v46 offset0:68 offset1:70
	ds_read2_b64 v[88:91], v33 offset0:100 offset1:102
	s_waitcnt lgkmcnt(5)
	v_mfma_f32_32x32x16_bf16 v[16:31], v[92:95], v[34:37], v[16:31]
	s_waitcnt lgkmcnt(4)
	v_mfma_f32_32x32x16_bf16 v[0:15], v[96:99], v[34:37], v[0:15]
	ds_read2_b64 v[34:37], v108 offset0:8 offset1:10
	ds_read2_b64 v[92:95], v109 offset0:40 offset1:42
	s_waitcnt lgkmcnt(5)
	v_mfma_f32_32x32x16_bf16 v[64:79], v[100:103], v[38:41], v[64:79]
	s_waitcnt lgkmcnt(4)
	v_mfma_f32_32x32x16_bf16 v[48:63], v[104:107], v[38:41], v[48:63]
	ds_read2_b64 v[96:99], v46 offset0:72 offset1:74
	ds_read2_b64 v[100:103], v33 offset0:104 offset1:106
	s_waitcnt lgkmcnt(5)
	v_mfma_f32_32x32x16_bf16 v[16:31], v[84:87], v[38:41], v[16:31]
	s_waitcnt lgkmcnt(4)
	v_mfma_f32_32x32x16_bf16 v[0:15], v[88:91], v[38:41], v[0:15]
	ds_read2_b64 v[38:41], v108 offset0:12 offset1:14
	ds_read2_b64 v[84:87], v109 offset0:44 offset1:46
	s_waitcnt lgkmcnt(5)
	v_mfma_f32_32x32x16_bf16 v[64:79], v[34:37], v[42:45], v[64:79]
	s_waitcnt lgkmcnt(4)
	v_mfma_f32_32x32x16_bf16 v[48:63], v[92:95], v[42:45], v[48:63]
	ds_read2_b64 v[34:37], v46 offset0:76 offset1:78
	ds_read2_b64 v[88:91], v33 offset0:108 offset1:110
	s_waitcnt lgkmcnt(5)
	v_mfma_f32_32x32x16_bf16 v[16:31], v[96:99], v[42:45], v[16:31]
	s_waitcnt lgkmcnt(4)
	v_mfma_f32_32x32x16_bf16 v[0:15], v[100:103], v[42:45], v[0:15]
	s_waitcnt lgkmcnt(3)
	v_mfma_f32_32x32x16_bf16 v[64:79], v[38:41], v[80:83], v[64:79]
	s_waitcnt lgkmcnt(2)
	v_mfma_f32_32x32x16_bf16 v[48:63], v[84:87], v[80:83], v[48:63]
	s_waitcnt lgkmcnt(1)
	v_mfma_f32_32x32x16_bf16 v[16:31], v[34:37], v[80:83], v[16:31]
	s_waitcnt lgkmcnt(0)
	v_mfma_f32_32x32x16_bf16 v[0:15], v[88:91], v[80:83], v[0:15]
